# stack21 + cache-policy: agent-scope write-through (sc1) on the residual epilogue's P stores so the full-barrier L2 write-back finds less dirty data
# baseline (speedup 1.0000x reference)
.LBB0_293:
	v_cvt_pk_bf16_f32 v176, v126, v127
	v_mul_f32_e32 v127, v127, v127
	v_fmac_f32_e32 v127, v126, v126
	v_mul_f32_e32 v126, v119, v119
	v_fmac_f32_e32 v126, v118, v118
	v_fmac_f32_e32 v127, v128, v128
	v_fmac_f32_e32 v126, v120, v120
	v_fmac_f32_e32 v127, v129, v129
	v_fmac_f32_e32 v126, v121, v121
	v_fmac_f32_e32 v127, v114, v114
	v_fmac_f32_e32 v126, v122, v122
	v_fmac_f32_e32 v127, v115, v115
	v_fmac_f32_e32 v126, v123, v123
	v_fmac_f32_e32 v127, v116, v116
	v_fmac_f32_e32 v126, v124, v124
	v_cvt_pk_bf16_f32 v177, v128, v129
	v_fmac_f32_e32 v127, v117, v117
	v_fmac_f32_e32 v126, v125, v125
	v_and_b32_e32 v128, 64, v158
	v_add_f32_e32 v127, v127, v126
	v_xor_b32_e32 v126, 16, v158
	v_add_u32_e32 v128, 64, v128
	v_cmp_lt_i32_e32 vcc, v126, v128
	v_cvt_pk_bf16_f32 v178, v114, v115
	v_xor_b32_e32 v114, 32, v158
	s_lshl_b32 s18, s3, 8
	v_cndmask_b32_e32 v126, v158, v126, vcc
	v_lshlrev_b32_e32 v126, 2, v126
	ds_bpermute_b32 v129, v126, v127
	v_cmp_lt_i32_e32 vcc, v114, v128
	v_and_b32_e32 v236, 15, v150
	v_bfe_u32 v237, v150, 4, 2
	v_lshrrev_b32_e32 v238, 2, v236
	v_lshl_or_b32 v237, v238, 2, v237
	v_and_b32_e32 v236, 3, v236
	v_lshlrev_b32_e32 v236, 3, v236
	v_and_or_b32 v238, v146, -16, v237
	v_lshrrev_b32_e32 v239, 5, v168
	v_lshl_or_b32 v239, v239, 5, v236
	v_cndmask_b32_e64 v238, v146, v238, s[100:101]
	v_cndmask_b32_e64 v239, v168, v239, s[100:101]
	v_add_u32_e32 v140, s18, v238
	v_cvt_pk_bf16_f32 v179, v116, v117
	v_ashrrev_i32_e32 v141, 31, v140
	v_cndmask_b32_e32 v114, v158, v114, vcc
	s_waitcnt lgkmcnt(0)
	v_add_f32_e32 v115, v127, v129
	v_lshlrev_b32_e32 v114, 2, v114
	ds_bpermute_b32 v116, v114, v115
	v_lshl_or_b32 v144, s2, 8, v239
	v_lshlrev_b64 v[142:143], 11, v[140:141]
	v_ashrrev_i32_e32 v145, 31, v144
	v_lshl_add_u64 v[142:143], s[10:11], 0, v[142:143]
	v_lshl_add_u64 v[142:143], v[144:145], 1, v[142:143]
	global_store_dwordx4 v[142:143], v[176:179], off sc1
	v_cvt_pk_bf16_f32 v118, v118, v119
	v_cvt_pk_bf16_f32 v119, v120, v121
	v_cvt_pk_bf16_f32 v120, v122, v123
	v_cvt_pk_bf16_f32 v121, v124, v125
	global_store_dwordx4 v[142:143], v[118:121], off offset:256 sc1
	s_and_saveexec_b64 s[54:55], s[4:5]
	s_cbranch_execz .LBB0_295
	s_waitcnt lgkmcnt(0)
	v_add_f32_e32 v115, v115, v116
	ds_write_b32 v165, v115
.LBB0_295:
	s_or_b64 exec, exec, s[54:55]
	s_waitcnt lgkmcnt(0)
	v_or_b32_e32 v116, 16, v140
	v_ashrrev_i32_e32 v117, 31, v116
	v_lshlrev_b64 v[116:117], 11, v[116:117]
	v_lshl_add_u64 v[116:117], s[10:11], 0, v[116:117]
	v_lshl_add_u64 v[120:121], v[144:145], 1, v[116:117]
	v_cvt_pk_bf16_f32 v116, v106, v107
	v_mul_f32_e32 v107, v107, v107
	v_fmac_f32_e32 v107, v106, v106
	v_mul_f32_e32 v106, v103, v103
	v_fmac_f32_e32 v106, v102, v102
	v_fmac_f32_e32 v107, v108, v108
	v_fmac_f32_e32 v106, v104, v104
	v_fmac_f32_e32 v107, v109, v109
	v_fmac_f32_e32 v106, v105, v105
	v_fmac_f32_e32 v107, v98, v98
	v_fmac_f32_e32 v106, v110, v110
	v_fmac_f32_e32 v107, v99, v99
	v_fmac_f32_e32 v106, v111, v111
	v_fmac_f32_e32 v107, v100, v100
	v_fmac_f32_e32 v106, v112, v112
	v_fmac_f32_e32 v107, v101, v101
	v_fmac_f32_e32 v106, v113, v113
	v_add_f32_e32 v106, v107, v106
	ds_bpermute_b32 v107, v126, v106
	v_cvt_pk_bf16_f32 v117, v108, v109
	v_cvt_pk_bf16_f32 v118, v98, v99
	v_cvt_pk_bf16_f32 v119, v100, v101
	global_store_dwordx4 v[120:121], v[116:119], off sc1
	s_waitcnt lgkmcnt(0)
	v_add_f32_e32 v98, v106, v107
	ds_bpermute_b32 v99, v114, v98
	v_cvt_pk_bf16_f32 v100, v102, v103
	v_cvt_pk_bf16_f32 v101, v104, v105
	v_cvt_pk_bf16_f32 v102, v110, v111
	v_cvt_pk_bf16_f32 v103, v112, v113
	global_store_dwordx4 v[120:121], v[100:103], off offset:256 sc1
	s_and_saveexec_b64 s[54:55], s[4:5]
	s_cbranch_execz .LBB0_297
	s_waitcnt lgkmcnt(0)
	v_add_f32_e32 v98, v98, v99
	ds_write_b32 v165, v98 offset:256
.LBB0_297:
	s_or_b64 exec, exec, s[54:55]
	v_or_b32_e32 v98, 32, v140
	s_waitcnt lgkmcnt(0)
	v_ashrrev_i32_e32 v99, 31, v98
	v_lshlrev_b64 v[98:99], 11, v[98:99]
	v_lshl_add_u64 v[98:99], s[10:11], 0, v[98:99]
	v_lshl_add_u64 v[102:103], v[144:145], 1, v[98:99]
	v_cvt_pk_bf16_f32 v98, v90, v91
	v_mul_f32_e32 v91, v91, v91
	v_fmac_f32_e32 v91, v90, v90
	v_mul_f32_e32 v90, v87, v87
	v_fmac_f32_e32 v90, v86, v86
	v_fmac_f32_e32 v91, v92, v92
	v_fmac_f32_e32 v90, v88, v88
	v_fmac_f32_e32 v91, v93, v93
	v_fmac_f32_e32 v90, v89, v89
	v_fmac_f32_e32 v91, v82, v82
	v_fmac_f32_e32 v90, v94, v94
	v_fmac_f32_e32 v91, v83, v83
	v_fmac_f32_e32 v90, v95, v95
	v_fmac_f32_e32 v91, v84, v84
	v_fmac_f32_e32 v90, v96, v96
	v_fmac_f32_e32 v91, v85, v85
	v_fmac_f32_e32 v90, v97, v97
	v_add_f32_e32 v90, v91, v90
	ds_bpermute_b32 v91, v126, v90
	v_cvt_pk_bf16_f32 v99, v92, v93
	v_cvt_pk_bf16_f32 v100, v82, v83
	v_cvt_pk_bf16_f32 v101, v84, v85
	global_store_dwordx4 v[102:103], v[98:101], off sc1
	s_waitcnt lgkmcnt(0)
	v_add_f32_e32 v82, v90, v91
	ds_bpermute_b32 v83, v114, v82
	v_cvt_pk_bf16_f32 v84, v86, v87
	v_cvt_pk_bf16_f32 v85, v88, v89
	v_cvt_pk_bf16_f32 v86, v94, v95
	v_cvt_pk_bf16_f32 v87, v96, v97
	global_store_dwordx4 v[102:103], v[84:87], off offset:256 sc1
	s_and_saveexec_b64 s[54:55], s[4:5]
	s_cbranch_execz .LBB0_299
	s_waitcnt lgkmcnt(0)
	v_add_f32_e32 v82, v82, v83
	ds_write_b32 v165, v82 offset:512
.LBB0_299:
	s_or_b64 exec, exec, s[54:55]
	v_or_b32_e32 v82, 48, v140
	s_waitcnt lgkmcnt(0)
	v_ashrrev_i32_e32 v83, 31, v82
	v_lshlrev_b64 v[82:83], 11, v[82:83]
	v_lshl_add_u64 v[82:83], s[10:11], 0, v[82:83]
	v_lshl_add_u64 v[86:87], v[144:145], 1, v[82:83]
	v_cvt_pk_bf16_f32 v82, v74, v75
	v_mul_f32_e32 v75, v75, v75
	v_fmac_f32_e32 v75, v74, v74
	v_mul_f32_e32 v74, v71, v71
	v_fmac_f32_e32 v74, v70, v70
	v_fmac_f32_e32 v75, v76, v76
	v_fmac_f32_e32 v74, v72, v72
	v_fmac_f32_e32 v75, v77, v77
	v_fmac_f32_e32 v74, v73, v73
	v_fmac_f32_e32 v75, v54, v54
	v_fmac_f32_e32 v74, v78, v78
	v_fmac_f32_e32 v75, v55, v55
	v_fmac_f32_e32 v74, v79, v79
	v_fmac_f32_e32 v75, v56, v56
	v_fmac_f32_e32 v74, v80, v80
	v_fmac_f32_e32 v75, v57, v57
	v_fmac_f32_e32 v74, v81, v81
	v_add_f32_e32 v74, v75, v74
	ds_bpermute_b32 v75, v126, v74
	v_cvt_pk_bf16_f32 v83, v76, v77
	v_cvt_pk_bf16_f32 v84, v54, v55
	v_cvt_pk_bf16_f32 v85, v56, v57
	global_store_dwordx4 v[86:87], v[82:85], off sc1
	s_waitcnt lgkmcnt(0)
	v_add_f32_e32 v54, v74, v75
	ds_bpermute_b32 v55, v114, v54
	v_cvt_pk_bf16_f32 v70, v70, v71
	v_cvt_pk_bf16_f32 v71, v72, v73
	v_cvt_pk_bf16_f32 v72, v78, v79
	v_cvt_pk_bf16_f32 v73, v80, v81
	global_store_dwordx4 v[86:87], v[70:73], off offset:256 sc1
	s_and_saveexec_b64 s[54:55], s[4:5]
	s_cbranch_execz .LBB0_301
	s_waitcnt lgkmcnt(0)
	v_add_f32_e32 v54, v54, v55
	ds_write_b32 v165, v54 offset:768
.LBB0_301:
	s_or_b64 exec, exec, s[54:55]
	v_cvt_pk_bf16_f32 v54, v58, v59
	v_mul_f32_e32 v59, v59, v59
	v_fmac_f32_e32 v59, v58, v58
	v_mul_f32_e32 v58, v51, v51
	v_fmac_f32_e32 v58, v50, v50
	v_fmac_f32_e32 v59, v60, v60
	v_fmac_f32_e32 v58, v52, v52
	v_fmac_f32_e32 v59, v61, v61
	v_fmac_f32_e32 v58, v53, v53
	v_fmac_f32_e32 v59, v62, v62
	v_fmac_f32_e32 v58, v66, v66
	v_fmac_f32_e32 v59, v63, v63
	v_fmac_f32_e32 v58, v67, v67
	v_fmac_f32_e32 v59, v64, v64
	v_fmac_f32_e32 v58, v68, v68
	v_fmac_f32_e32 v59, v65, v65
	v_fmac_f32_e32 v58, v69, v69
	v_add_f32_e32 v58, v59, v58
	ds_bpermute_b32 v59, v126, v58
	v_add_co_u32_e32 v72, vcc, 0x40000, v142
	s_waitcnt lgkmcnt(0)
	v_cvt_pk_bf16_f32 v55, v60, v61
	v_cvt_pk_bf16_f32 v56, v62, v63
	v_cvt_pk_bf16_f32 v57, v64, v65
	v_lshl_add_u64 v[70:71], v[142:143], 0, s[90:91]
	v_addc_co_u32_e32 v73, vcc, 0, v143, vcc
	global_store_dwordx4 v[72:73], v[54:57], off sc1
	s_nop 1
	v_cvt_pk_bf16_f32 v54, v50, v51
	v_add_f32_e32 v50, v58, v59
	ds_bpermute_b32 v51, v114, v50
	v_cvt_pk_bf16_f32 v55, v52, v53
	v_cvt_pk_bf16_f32 v56, v66, v67
	v_cvt_pk_bf16_f32 v57, v68, v69
	global_store_dwordx4 v[70:71], v[54:57], off offset:256 sc1
	s_and_saveexec_b64 s[54:55], s[4:5]
	s_cbranch_execz .LBB0_303
	s_waitcnt lgkmcnt(0)
	v_add_f32_e32 v50, v50, v51
	ds_write_b32 v167, v50
.LBB0_303:
	s_or_b64 exec, exec, s[54:55]
	v_cvt_pk_bf16_f32 v50, v38, v39
	v_mul_f32_e32 v39, v39, v39
	v_fmac_f32_e32 v39, v38, v38
	v_mul_f32_e32 v38, v35, v35
	v_fmac_f32_e32 v38, v34, v34
	v_fmac_f32_e32 v39, v40, v40
	v_fmac_f32_e32 v38, v36, v36
	v_fmac_f32_e32 v39, v41, v41
	v_fmac_f32_e32 v38, v37, v37
	v_fmac_f32_e32 v39, v42, v42
	v_fmac_f32_e32 v38, v46, v46
	v_fmac_f32_e32 v39, v43, v43
	v_fmac_f32_e32 v38, v47, v47
	v_fmac_f32_e32 v39, v44, v44
	v_fmac_f32_e32 v38, v48, v48
	v_fmac_f32_e32 v39, v45, v45
	v_fmac_f32_e32 v38, v49, v49
	v_add_f32_e32 v39, v39, v38
	s_waitcnt lgkmcnt(0)
	v_cvt_pk_bf16_f32 v51, v40, v41
	ds_bpermute_b32 v40, v126, v39
	v_add_co_u32_e32 v56, vcc, 0x48000, v142
	v_cvt_pk_bf16_f32 v52, v42, v43
	v_cvt_pk_bf16_f32 v53, v44, v45
	v_lshl_add_u64 v[54:55], v[142:143], 0, s[92:93]
	s_nop 0
	v_addc_co_u32_e32 v57, vcc, 0, v143, vcc
	global_store_dwordx4 v[56:57], v[50:53], off sc1
	v_cvt_pk_bf16_f32 v38, v34, v35
	s_waitcnt lgkmcnt(0)
	v_add_f32_e32 v34, v39, v40
	ds_bpermute_b32 v35, v114, v34
	v_cvt_pk_bf16_f32 v39, v36, v37
	v_cvt_pk_bf16_f32 v40, v46, v47
	v_cvt_pk_bf16_f32 v41, v48, v49
	global_store_dwordx4 v[54:55], v[38:41], off offset:256 sc1
	s_and_saveexec_b64 s[54:55], s[4:5]
	s_cbranch_execz .LBB0_305
	s_waitcnt lgkmcnt(0)
	v_add_f32_e32 v34, v34, v35
	ds_write_b32 v165, v34 offset:2304
.LBB0_305:
	s_or_b64 exec, exec, s[54:55]
	v_cvt_pk_bf16_f32 v34, v18, v19
	v_mul_f32_e32 v19, v19, v19
	v_fmac_f32_e32 v19, v18, v18
	v_mul_f32_e32 v18, v15, v15
	v_fmac_f32_e32 v18, v14, v14
	v_fmac_f32_e32 v19, v20, v20
	v_fmac_f32_e32 v18, v16, v16
	v_fmac_f32_e32 v19, v21, v21
	v_fmac_f32_e32 v18, v17, v17
	v_fmac_f32_e32 v19, v26, v26
	v_fmac_f32_e32 v18, v30, v30
	v_fmac_f32_e32 v19, v27, v27
	v_fmac_f32_e32 v18, v31, v31
	v_fmac_f32_e32 v19, v28, v28
	v_fmac_f32_e32 v18, v32, v32
	v_fmac_f32_e32 v19, v29, v29
	v_fmac_f32_e32 v18, v33, v33
	v_add_f32_e32 v19, v19, v18
	s_waitcnt lgkmcnt(0)
	v_cvt_pk_bf16_f32 v35, v20, v21
	ds_bpermute_b32 v20, v126, v19
	v_add_co_u32_e32 v40, vcc, 0x50000, v142
	v_cvt_pk_bf16_f32 v36, v26, v27
	v_cvt_pk_bf16_f32 v37, v28, v29
	v_lshl_add_u64 v[38:39], v[142:143], 0, s[98:99]
	s_nop 0
	v_addc_co_u32_e32 v41, vcc, 0, v143, vcc
	global_store_dwordx4 v[40:41], v[34:37], off sc1
	v_cvt_pk_bf16_f32 v18, v14, v15
	s_waitcnt lgkmcnt(0)
	v_add_f32_e32 v14, v19, v20
	ds_bpermute_b32 v15, v114, v14
	v_cvt_pk_bf16_f32 v19, v16, v17
	v_cvt_pk_bf16_f32 v20, v30, v31
	v_cvt_pk_bf16_f32 v21, v32, v33
	global_store_dwordx4 v[38:39], v[18:21], off offset:256 sc1
	s_and_saveexec_b64 s[54:55], s[4:5]
	s_cbranch_execz .LBB0_307
	s_waitcnt lgkmcnt(0)
	v_add_f32_e32 v14, v14, v15
	ds_write_b32 v165, v14 offset:2560
.LBB0_307:
	s_or_b64 exec, exec, s[54:55]
	v_cvt_pk_bf16_f32 v14, v2, v3
	v_mul_f32_e32 v3, v3, v3
	v_fmac_f32_e32 v3, v2, v2
	v_mul_f32_e32 v2, v11, v11
	v_fmac_f32_e32 v2, v10, v10
	v_fmac_f32_e32 v3, v4, v4
	v_fmac_f32_e32 v2, v12, v12
	v_fmac_f32_e32 v3, v5, v5
	v_fmac_f32_e32 v2, v13, v13
	v_fmac_f32_e32 v3, v6, v6
	v_fmac_f32_e32 v2, v22, v22
	v_fmac_f32_e32 v3, v7, v7
	v_fmac_f32_e32 v2, v23, v23
	v_fmac_f32_e32 v3, v8, v8
	v_fmac_f32_e32 v2, v24, v24
	v_fmac_f32_e32 v3, v9, v9
	v_fmac_f32_e32 v2, v25, v25
	v_add_f32_e32 v2, v3, v2
	ds_bpermute_b32 v3, v126, v2
	s_mov_b64 s[30:31], 0x58000
	v_add_co_u32_e32 v20, vcc, 0x58000, v142
	v_lshl_add_u64 v[18:19], v[142:143], 0, s[30:31]
	s_waitcnt lgkmcnt(0)
	v_add_f32_e32 v2, v2, v3
	ds_bpermute_b32 v3, v114, v2
	v_addc_co_u32_e32 v21, vcc, 0, v143, vcc
	v_cvt_pk_bf16_f32 v15, v4, v5
	v_cvt_pk_bf16_f32 v16, v6, v7
	v_cvt_pk_bf16_f32 v17, v8, v9
	global_store_dwordx4 v[20:21], v[14:17], off sc1
	v_cvt_pk_bf16_f32 v4, v10, v11
	v_cvt_pk_bf16_f32 v5, v12, v13
	v_cvt_pk_bf16_f32 v6, v22, v23
	v_cvt_pk_bf16_f32 v7, v24, v25
	global_store_dwordx4 v[18:19], v[4:7], off offset:256 sc1
	s_and_saveexec_b64 s[54:55], s[4:5]
	s_cbranch_execz .LBB0_309
	s_waitcnt lgkmcnt(0)
	v_add_f32_e32 v2, v2, v3
	ds_write_b32 v165, v2 offset:2816
